# P0 rmsnorm: the 15 norm-weight loads of a row issued up front with the x loads (one wait) instead of a load/wait/store ladder
# speedup vs baseline: 1.0033x; 1.0033x over previous
; DI void rms_row_to_bf16(const float* xrow, const float* w, bf16* orow, int lane) {
;     const f32x4* xr = (const f32x4*)xrow + lane; const f32x4* wr = (const f32x4*)w + lane;
;     f32x4 v[16]; float s = 0.f;
; #pragma unroll
;     for (int j = 0; j < 16; ++j) { v[j] = xr[64 * j]; s += (v[j].x * v[j].x + v[j].y * v[j].y) + (v[j].z * v[j].z + v[j].w * v[j].w); }
.LBB0_18:
	global_load_dwordx4 v[14:17], v[88:89], off nt
	global_load_dwordx4 v[10:13], v[88:89], off offset:1024 nt
	global_load_dwordx4 v[6:9], v[88:89], off offset:2048 nt
	global_load_dwordx4 v[2:5], v[88:89], off offset:3072 nt
	v_add_co_u32_e32 v18, vcc, s3, v88
	s_add_i32 s4, s4, s6
	s_nop 0
	v_addc_co_u32_e32 v19, vcc, 0, v89, vcc
	v_add_co_u32_e32 v20, vcc, s5, v88
	s_cmpk_lt_i32 s4, 0x4000
	s_nop 0
	v_addc_co_u32_e32 v21, vcc, 0, v89, vcc
	v_add_co_u32_e32 v22, vcc, s7, v88
	s_waitcnt vmcnt(3)
	v_pk_mul_f32 v[108:109], v[16:17], v[16:17]
	v_addc_co_u32_e32 v23, vcc, 0, v89, vcc
	global_load_dwordx4 v[100:103], v[62:63], off
	global_load_dwordx4 v[104:107], v[20:21], off offset:-4096 nt
	global_load_dwordx4 v[54:57], v[18:19], off offset:2048 nt
	global_load_dwordx4 v[58:61], v[18:19], off offset:1024 nt
	global_load_dwordx4 v[50:53], v[18:19], off offset:3072 nt
	global_load_dwordx4 v[42:45], v[20:21], off offset:1024 nt
	global_load_dwordx4 v[46:49], v[20:21], off nt
	global_load_dwordx4 v[38:41], v[20:21], off offset:2048 nt
	global_load_dwordx4 v[30:33], v[22:23], off nt
	global_load_dwordx4 v[34:37], v[20:21], off offset:3072 nt
	global_load_dwordx4 v[26:29], v[22:23], off offset:1024 nt
	s_nop 0
	global_load_dwordx4 v[18:21], v[22:23], off offset:3072 nt
	s_nop 0
	global_load_dwordx4 v[22:25], v[22:23], off offset:2048 nt
	global_load_dwordx4 v[168:171], v[62:63], off offset:1024
	global_load_dwordx4 v[172:175], v[62:63], off offset:2048
	global_load_dwordx4 v[176:179], v[62:63], off offset:3072
	global_load_dwordx4 v[180:183], v[64:65], off
	global_load_dwordx4 v[184:187], v[66:67], off
	global_load_dwordx4 v[188:191], v[68:69], off
	global_load_dwordx4 v[192:195], v[70:71], off
	global_load_dwordx4 v[196:199], v[72:73], off
	global_load_dwordx4 v[200:203], v[74:75], off
	global_load_dwordx4 v[204:207], v[76:77], off
	global_load_dwordx4 v[208:211], v[78:79], off
	global_load_dwordx4 v[212:215], v[80:81], off
	global_load_dwordx4 v[216:219], v[82:83], off
	global_load_dwordx4 v[220:223], v[84:85], off
	global_load_dwordx4 v[224:227], v[86:87], off
	v_pk_mul_f32 v[110:111], v[14:15], v[14:15]
	s_waitcnt vmcnt(30)
	v_pk_mul_f32 v[112:113], v[12:13], v[12:13]
	v_pk_mul_f32 v[114:115], v[10:11], v[10:11]
	v_pk_mov_b32 v[118:119], v[110:111], v[108:109] op_sel:[1,0]
	v_mov_b32_e32 v111, v109
	v_pk_mov_b32 v[108:109], v[114:115], v[112:113] op_sel:[1,0]
	v_mov_b32_e32 v115, v113
	s_waitcnt vmcnt(29)
	v_mul_f32_e32 v92, v7, v7
	v_mul_f32_e32 v116, v9, v9
	v_pk_add_f32 v[110:111], v[118:119], v[110:111]
	v_pk_add_f32 v[108:109], v[108:109], v[114:115]
	s_waitcnt vmcnt(28)
	v_mul_f32_e32 v99, v2, v2
	v_mul_f32_e32 v149, v3, v3
	v_mul_f32_e32 v125, v4, v4
	v_mul_f32_e32 v131, v5, v5
	v_pk_fma_f32 v[112:113], v[6:7], v[6:7], v[92:93] op_sel_hi:[1,1,0]
	v_pk_fma_f32 v[116:117], v[8:9], v[8:9], v[116:117] op_sel_hi:[1,1,0]
	v_pk_add_f32 v[110:111], v[110:111], v[110:111] op_sel:[0,1] op_sel_hi:[1,0]
	v_pk_add_f32 v[108:109], v[108:109], v[108:109] op_sel:[0,1] op_sel_hi:[1,0]
	v_mov_b32_e32 v113, v125
	v_mov_b32_e32 v117, v131
	v_mov_b32_e32 v111, v99
	v_mov_b32_e32 v109, v149
	v_pk_add_f32 v[112:113], v[112:113], v[116:117]
	v_pk_add_f32 v[108:109], v[110:111], v[108:109]
	v_lshl_add_u64 v[88:89], v[88:89], 0, s[8:9]
	v_pk_add_f32 v[108:109], v[108:109], v[112:113]
	s_waitcnt vmcnt(26)
	v_pk_mul_f32 v[120:121], v[106:107], v[106:107]
	v_pk_mul_f32 v[122:123], v[104:105], v[104:105]
	s_waitcnt vmcnt(24)
	v_mul_f32_e32 v92, v59, v59
	v_pk_mov_b32 v[114:115], v[122:123], v[120:121] op_sel:[1,0]
	v_mov_b32_e32 v123, v121
	v_mul_f32_e32 v124, v61, v61
	v_pk_add_f32 v[114:115], v[114:115], v[122:123]
	v_mul_f32_e32 v150, v54, v54
	v_mul_f32_e32 v151, v55, v55
	v_mul_f32_e32 v152, v56, v56
	v_mul_f32_e32 v153, v57, v57
	v_pk_fma_f32 v[118:119], v[58:59], v[58:59], v[92:93] op_sel_hi:[1,1,0]
	v_pk_fma_f32 v[120:121], v[60:61], v[60:61], v[124:125] op_sel_hi:[1,1,0]
	v_pk_add_f32 v[114:115], v[114:115], v[114:115] op_sel:[0,1] op_sel_hi:[1,0]
	v_pk_add_f32 v[108:109], v[108:109], v[108:109] op_sel:[0,1] op_sel_hi:[1,0]
	s_waitcnt vmcnt(23)
	v_pk_mul_f32 v[126:127], v[52:53], v[52:53]
	v_pk_mul_f32 v[128:129], v[50:51], v[50:51]
	v_mov_b32_e32 v119, v152
	v_mov_b32_e32 v121, v153
	v_mov_b32_e32 v115, v151
	v_mov_b32_e32 v109, v150
	v_pk_mov_b32 v[124:125], v[128:129], v[126:127] op_sel:[1,0]
	v_mov_b32_e32 v129, v127
	v_pk_add_f32 v[118:119], v[118:119], v[120:121]
	v_pk_add_f32 v[108:109], v[108:109], v[114:115]
	s_waitcnt vmcnt(21)
	v_mul_f32_e32 v130, v47, v47
	v_mul_f32_e32 v132, v49, v49
	v_pk_add_f32 v[116:117], v[124:125], v[128:129]
	v_pk_add_f32 v[108:109], v[108:109], v[118:119]
	v_mul_f32_e32 v154, v42, v42
	v_mul_f32_e32 v155, v43, v43
	v_mul_f32_e32 v156, v44, v44
	v_mul_f32_e32 v157, v45, v45
	v_pk_fma_f32 v[126:127], v[46:47], v[46:47], v[130:131] op_sel_hi:[1,1,0]
	v_pk_fma_f32 v[130:131], v[48:49], v[48:49], v[132:133] op_sel_hi:[1,1,0]
	v_pk_add_f32 v[116:117], v[116:117], v[116:117] op_sel:[0,1] op_sel_hi:[1,0]
	v_pk_add_f32 v[108:109], v[108:109], v[108:109] op_sel:[0,1] op_sel_hi:[1,0]
	s_waitcnt vmcnt(20)
	v_pk_mul_f32 v[134:135], v[40:41], v[40:41]
	v_pk_mul_f32 v[136:137], v[38:39], v[38:39]
	v_mov_b32_e32 v127, v156
	v_mov_b32_e32 v131, v157
	v_mov_b32_e32 v117, v155
	v_mov_b32_e32 v109, v154
	v_pk_mov_b32 v[132:133], v[136:137], v[134:135] op_sel:[1,0]
	v_mov_b32_e32 v137, v135
	v_pk_add_f32 v[120:121], v[126:127], v[130:131]
	v_pk_add_f32 v[108:109], v[108:109], v[116:117]
	s_waitcnt vmcnt(18)
; DI float wave_sum(float v) {
; #pragma unroll
;     for (int o = 1; o < 64; o <<= 1) v += __shfl_xor(v, o);
;     return v;
; DI void rms_row_to_bf16(const float* xrow, const float* w, bf16* orow, int lane) {
;     ...
;     for (int j = 0; j < 16; ++j) { v[j] = xr[64 * j]; s += (v[j].x * v[j].x + v[j].y * v[j].y) + (v[j].z * v[j].z + v[j].w * v[j].w); }
;     const float rstd = __builtin_amdgcn_rsqf(wave_sum(s) * (1.f / 4096.f) + EPS);
	v_mul_f32_e32 v138, v35, v35
	v_mul_f32_e32 v140, v37, v37
	v_pk_add_f32 v[122:123], v[132:133], v[136:137]
	v_pk_add_f32 v[108:109], v[108:109], v[120:121]
	v_mul_f32_e32 v158, v30, v30
	v_mul_f32_e32 v159, v31, v31
	v_mul_f32_e32 v160, v32, v32
	v_mul_f32_e32 v161, v33, v33
	v_pk_fma_f32 v[134:135], v[34:35], v[34:35], v[138:139] op_sel_hi:[1,1,0]
	v_pk_fma_f32 v[138:139], v[36:37], v[36:37], v[140:141] op_sel_hi:[1,1,0]
	v_pk_add_f32 v[122:123], v[122:123], v[122:123] op_sel:[0,1] op_sel_hi:[1,0]
	v_pk_add_f32 v[108:109], v[108:109], v[108:109] op_sel:[0,1] op_sel_hi:[1,0]
	s_waitcnt vmcnt(17)
	v_pk_mul_f32 v[142:143], v[28:29], v[28:29]
	v_pk_mul_f32 v[144:145], v[26:27], v[26:27]
	v_mov_b32_e32 v135, v160
	v_mov_b32_e32 v139, v161
	v_mov_b32_e32 v123, v159
	v_mov_b32_e32 v109, v158
	v_pk_mov_b32 v[140:141], v[144:145], v[142:143] op_sel:[1,0]
	v_mov_b32_e32 v145, v143
	v_pk_add_f32 v[126:127], v[134:135], v[138:139]
	v_pk_add_f32 v[108:109], v[108:109], v[122:123]
	s_waitcnt vmcnt(0)
	v_mul_f32_e32 v146, v23, v23
	v_mul_f32_e32 v148, v25, v25
	v_pk_add_f32 v[124:125], v[140:141], v[144:145]
	v_pk_add_f32 v[108:109], v[108:109], v[126:127]
	v_mul_f32_e32 v162, v18, v18
	v_mul_f32_e32 v163, v19, v19
	v_mul_f32_e32 v164, v20, v20
	v_mul_f32_e32 v165, v21, v21
	v_pk_fma_f32 v[142:143], v[22:23], v[22:23], v[146:147] op_sel_hi:[1,1,0]
	v_pk_fma_f32 v[146:147], v[24:25], v[24:25], v[148:149] op_sel_hi:[1,1,0]
	v_pk_add_f32 v[124:125], v[124:125], v[124:125] op_sel:[0,1] op_sel_hi:[1,0]
	v_pk_add_f32 v[108:109], v[108:109], v[108:109] op_sel:[0,1] op_sel_hi:[1,0]
	v_mov_b32_e32 v143, v164
	v_mov_b32_e32 v147, v165
	v_mov_b32_e32 v125, v163
	v_mov_b32_e32 v109, v162
	v_pk_add_f32 v[128:129], v[142:143], v[146:147]
	v_pk_add_f32 v[108:109], v[108:109], v[124:125]
	s_nop 0
	v_pk_add_f32 v[108:109], v[108:109], v[128:129]
	s_nop 0
	v_add_f32_e32 v92, v108, v109
	ds_bpermute_b32 v99, v1, v92
	s_waitcnt lgkmcnt(0)
	v_add_f32_e32 v92, v92, v99
	ds_bpermute_b32 v99, v93, v92
	s_waitcnt lgkmcnt(0)
	v_add_f32_e32 v92, v92, v99
	ds_bpermute_b32 v99, v94, v92
	s_waitcnt lgkmcnt(0)
	v_add_f32_e32 v92, v92, v99
	ds_bpermute_b32 v99, v95, v92
	s_waitcnt lgkmcnt(0)
	v_add_f32_e32 v92, v92, v99
	ds_bpermute_b32 v99, v96, v92
	s_waitcnt lgkmcnt(0)
	v_add_f32_e32 v92, v92, v99
	ds_bpermute_b32 v99, v97, v92
	s_waitcnt lgkmcnt(0)
; DI unsigned pk2(float lo, float hi) { f32x2 v = {lo, hi}; bf16v2 b = __builtin_convertvector(v, bf16v2); return __builtin_bit_cast(unsigned, b); }
; DI void rms_row_to_bf16(const float* xrow, const float* w, bf16* orow, int lane) {
;     ...
;     const float rstd = __builtin_amdgcn_rsqf(wave_sum(s) * (1.f / 4096.f) + EPS);
;     u32x2* o8 = (u32x2*)orow + lane;
; #pragma unroll
;     for (int j = 0; j < 16; ++j) { const f32x4 ww = wr[64 * j]; u32x2 p; p.x = pk2(v[j].x * rstd * ww.x, v[j].y * rstd * ww.y); p.y = pk2(v[j].z * rstd * ww.z, v[j].w * rstd * ww.w); o8[64 * j] = p; }
	v_add_f32_e32 v92, v92, v99
	v_fmamk_f32 v92, v92, 0x39800000, v98
	v_rsq_f32_e32 v92, v92
	s_nop 0
	v_pk_mul_f32 v[14:15], v[14:15], v[92:93] op_sel_hi:[1,0]
	v_pk_mul_f32 v[16:17], v[16:17], v[92:93] op_sel_hi:[1,0]
	v_pk_mul_f32 v[14:15], v[100:101], v[14:15]
	v_pk_mul_f32 v[16:17], v[102:103], v[16:17]
	v_cvt_pk_bf16_f32 v14, v14, v15
	v_cvt_pk_bf16_f32 v15, v16, v17
	global_store_dwordx2 v[90:91], v[14:15], off
	v_mov_b32_e32 v14, v168
	v_mov_b32_e32 v15, v169
	v_mov_b32_e32 v16, v170
	v_mov_b32_e32 v17, v171
	v_pk_mul_f32 v[10:11], v[10:11], v[92:93] op_sel_hi:[1,0]
	v_pk_mul_f32 v[12:13], v[12:13], v[92:93] op_sel_hi:[1,0]
	v_pk_mul_f32 v[6:7], v[6:7], v[92:93] op_sel_hi:[1,0]
	v_pk_mul_f32 v[8:9], v[8:9], v[92:93] op_sel_hi:[1,0]
	v_pk_mul_f32 v[2:3], v[2:3], v[92:93] op_sel_hi:[1,0]
	v_pk_mul_f32 v[4:5], v[4:5], v[92:93] op_sel_hi:[1,0]
	s_nop 0
	v_pk_mul_f32 v[10:11], v[14:15], v[10:11]
	v_pk_mul_f32 v[12:13], v[16:17], v[12:13]
	v_cvt_pk_bf16_f32 v10, v10, v11
	v_cvt_pk_bf16_f32 v11, v12, v13
	global_store_dwordx2 v[90:91], v[10:11], off offset:512
	v_mov_b32_e32 v10, v172
	v_mov_b32_e32 v11, v173
	v_mov_b32_e32 v12, v174
	v_mov_b32_e32 v13, v175
	s_nop 0
	v_pk_mul_f32 v[6:7], v[10:11], v[6:7]
	v_pk_mul_f32 v[8:9], v[12:13], v[8:9]
	v_cvt_pk_bf16_f32 v6, v6, v7
	v_cvt_pk_bf16_f32 v7, v8, v9
	global_store_dwordx2 v[90:91], v[6:7], off offset:1024
	v_mov_b32_e32 v6, v176
	v_mov_b32_e32 v7, v177
	v_mov_b32_e32 v8, v178
	v_mov_b32_e32 v9, v179
	v_pk_mul_f32 v[10:11], v[48:49], v[92:93] op_sel_hi:[1,0]
	s_nop 0
	v_pk_mul_f32 v[2:3], v[6:7], v[2:3]
	v_pk_mul_f32 v[4:5], v[8:9], v[4:5]
	v_cvt_pk_bf16_f32 v2, v2, v3
	v_cvt_pk_bf16_f32 v3, v4, v5
	global_store_dwordx2 v[90:91], v[2:3], off offset:1536
	v_mov_b32_e32 v2, v180
	v_mov_b32_e32 v3, v181
	v_mov_b32_e32 v4, v182
	v_mov_b32_e32 v5, v183
	v_pk_mul_f32 v[6:7], v[104:105], v[92:93] op_sel_hi:[1,0]
	v_pk_mul_f32 v[8:9], v[106:107], v[92:93] op_sel_hi:[1,0]
	s_nop 0
	v_pk_mul_f32 v[2:3], v[6:7], v[2:3]
	v_pk_mul_f32 v[4:5], v[8:9], v[4:5]
	v_cvt_pk_bf16_f32 v2, v2, v3
	v_cvt_pk_bf16_f32 v3, v4, v5
	global_store_dwordx2 v[90:91], v[2:3], off offset:2048
	v_mov_b32_e32 v2, v184
	v_mov_b32_e32 v3, v185
	v_mov_b32_e32 v4, v186
	v_mov_b32_e32 v5, v187
	v_pk_mul_f32 v[6:7], v[58:59], v[92:93] op_sel_hi:[1,0]
	v_pk_mul_f32 v[8:9], v[60:61], v[92:93] op_sel_hi:[1,0]
	s_nop 0
	v_pk_mul_f32 v[2:3], v[6:7], v[2:3]
	v_pk_mul_f32 v[4:5], v[8:9], v[4:5]
	v_cvt_pk_bf16_f32 v2, v2, v3
	v_cvt_pk_bf16_f32 v3, v4, v5
	global_store_dwordx2 v[90:91], v[2:3], off offset:2560
	v_mov_b32_e32 v2, v188
	v_mov_b32_e32 v3, v189
	v_mov_b32_e32 v4, v190
	v_mov_b32_e32 v5, v191
	v_pk_mul_f32 v[6:7], v[54:55], v[92:93] op_sel_hi:[1,0]
	v_pk_mul_f32 v[8:9], v[56:57], v[92:93] op_sel_hi:[1,0]
	s_nop 0
	v_pk_mul_f32 v[2:3], v[6:7], v[2:3]
	v_pk_mul_f32 v[4:5], v[8:9], v[4:5]
	v_cvt_pk_bf16_f32 v2, v2, v3
	v_cvt_pk_bf16_f32 v3, v4, v5
	global_store_dwordx2 v[90:91], v[2:3], off offset:3072
	v_mov_b32_e32 v2, v192
	v_mov_b32_e32 v3, v193
	v_mov_b32_e32 v4, v194
	v_mov_b32_e32 v5, v195
	v_pk_mul_f32 v[6:7], v[50:51], v[92:93] op_sel_hi:[1,0]
	v_pk_mul_f32 v[8:9], v[52:53], v[92:93] op_sel_hi:[1,0]
	s_nop 0
	v_pk_mul_f32 v[2:3], v[6:7], v[2:3]
	v_pk_mul_f32 v[4:5], v[8:9], v[4:5]
	v_cvt_pk_bf16_f32 v2, v2, v3
	v_cvt_pk_bf16_f32 v3, v4, v5
	global_store_dwordx2 v[90:91], v[2:3], off offset:3584
	v_mov_b32_e32 v2, v196
	v_mov_b32_e32 v3, v197
	v_mov_b32_e32 v4, v198
	v_mov_b32_e32 v5, v199
	v_pk_mul_f32 v[8:9], v[46:47], v[92:93] op_sel_hi:[1,0]
	v_add_co_u32_e32 v6, vcc, s3, v90
	s_nop 0
	v_pk_mul_f32 v[2:3], v[8:9], v[2:3]
	v_pk_mul_f32 v[4:5], v[10:11], v[4:5]
	v_addc_co_u32_e32 v7, vcc, 0, v91, vcc
	v_cvt_pk_bf16_f32 v2, v2, v3
	v_cvt_pk_bf16_f32 v3, v4, v5
	global_store_dwordx2 v[6:7], v[2:3], off
	v_mov_b32_e32 v2, v200
	v_mov_b32_e32 v3, v201
	v_mov_b32_e32 v4, v202
	v_mov_b32_e32 v5, v203
	v_pk_mul_f32 v[8:9], v[42:43], v[92:93] op_sel_hi:[1,0]
	v_pk_mul_f32 v[10:11], v[44:45], v[92:93] op_sel_hi:[1,0]
	v_lshl_add_u64 v[90:91], v[90:91], 0, s[10:11]
	s_nop 0
	v_pk_mul_f32 v[2:3], v[8:9], v[2:3]
	v_pk_mul_f32 v[4:5], v[10:11], v[4:5]
	v_cvt_pk_bf16_f32 v2, v2, v3
	v_cvt_pk_bf16_f32 v3, v4, v5
	global_store_dwordx2 v[6:7], v[2:3], off offset:512
	v_mov_b32_e32 v2, v204
	v_mov_b32_e32 v3, v205
	v_mov_b32_e32 v4, v206
	v_mov_b32_e32 v5, v207
	v_pk_mul_f32 v[8:9], v[38:39], v[92:93] op_sel_hi:[1,0]
	v_pk_mul_f32 v[10:11], v[40:41], v[92:93] op_sel_hi:[1,0]
	s_nop 0
	v_pk_mul_f32 v[2:3], v[8:9], v[2:3]
	v_pk_mul_f32 v[4:5], v[10:11], v[4:5]
	v_cvt_pk_bf16_f32 v2, v2, v3
	v_cvt_pk_bf16_f32 v3, v4, v5
	global_store_dwordx2 v[6:7], v[2:3], off offset:1024
	v_mov_b32_e32 v2, v208
	v_mov_b32_e32 v3, v209
	v_mov_b32_e32 v4, v210
	v_mov_b32_e32 v5, v211
	v_pk_mul_f32 v[8:9], v[34:35], v[92:93] op_sel_hi:[1,0]
	v_pk_mul_f32 v[10:11], v[36:37], v[92:93] op_sel_hi:[1,0]
	s_nop 0
	v_pk_mul_f32 v[2:3], v[8:9], v[2:3]
	v_pk_mul_f32 v[4:5], v[10:11], v[4:5]
	v_cvt_pk_bf16_f32 v2, v2, v3
	v_cvt_pk_bf16_f32 v3, v4, v5
	global_store_dwordx2 v[6:7], v[2:3], off offset:1536
	v_mov_b32_e32 v2, v212
	v_mov_b32_e32 v3, v213
	v_mov_b32_e32 v4, v214
	v_mov_b32_e32 v5, v215
	v_pk_mul_f32 v[8:9], v[30:31], v[92:93] op_sel_hi:[1,0]
	v_pk_mul_f32 v[10:11], v[32:33], v[92:93] op_sel_hi:[1,0]
	s_nop 0
	v_pk_mul_f32 v[2:3], v[8:9], v[2:3]
	v_pk_mul_f32 v[4:5], v[10:11], v[4:5]
	v_cvt_pk_bf16_f32 v2, v2, v3
	v_cvt_pk_bf16_f32 v3, v4, v5
	global_store_dwordx2 v[6:7], v[2:3], off offset:2048
	v_mov_b32_e32 v2, v216
	v_mov_b32_e32 v3, v217
	v_mov_b32_e32 v4, v218
	v_mov_b32_e32 v5, v219
	v_pk_mul_f32 v[8:9], v[26:27], v[92:93] op_sel_hi:[1,0]
	v_pk_mul_f32 v[10:11], v[28:29], v[92:93] op_sel_hi:[1,0]
	s_nop 0
	v_pk_mul_f32 v[2:3], v[8:9], v[2:3]
	v_pk_mul_f32 v[4:5], v[10:11], v[4:5]
	v_cvt_pk_bf16_f32 v2, v2, v3
	v_cvt_pk_bf16_f32 v3, v4, v5
	global_store_dwordx2 v[6:7], v[2:3], off offset:2560
	v_mov_b32_e32 v2, v220
	v_mov_b32_e32 v3, v221
	v_mov_b32_e32 v4, v222
	v_mov_b32_e32 v5, v223
	v_pk_mul_f32 v[8:9], v[22:23], v[92:93] op_sel_hi:[1,0]
	v_pk_mul_f32 v[10:11], v[24:25], v[92:93] op_sel_hi:[1,0]
	s_nop 0
	v_pk_mul_f32 v[2:3], v[8:9], v[2:3]
	v_pk_mul_f32 v[4:5], v[10:11], v[4:5]
	v_cvt_pk_bf16_f32 v2, v2, v3
	v_cvt_pk_bf16_f32 v3, v4, v5
	global_store_dwordx2 v[6:7], v[2:3], off offset:3072
	v_mov_b32_e32 v2, v224
	v_mov_b32_e32 v3, v225
	v_mov_b32_e32 v4, v226
	v_mov_b32_e32 v5, v227
	v_pk_mul_f32 v[8:9], v[18:19], v[92:93] op_sel_hi:[1,0]
	v_pk_mul_f32 v[10:11], v[20:21], v[92:93] op_sel_hi:[1,0]
	s_nop 0
	v_pk_mul_f32 v[2:3], v[8:9], v[2:3]
	v_pk_mul_f32 v[4:5], v[10:11], v[4:5]
	v_cvt_pk_bf16_f32 v2, v2, v3
	v_cvt_pk_bf16_f32 v3, v4, v5
	global_store_dwordx2 v[6:7], v[2:3], off offset:3584
	s_cbranch_scc1 .LBB0_18
